# P2: one work queue per XCD (XCC id), with fallback stealing; each XCD queue holds 6 (batch,head) K/V panels with their 8 query tiles so panel re-reads share an L2
# baseline (speedup 1.0000x reference)
.LBB0_167:
	v_lshl_add_u64 v[78:79], v[74:75], 0, s[6:7]
	s_mov_b64 s[2:3], 0xc000
	v_lshl_add_u64 v[82:83], v[78:79], 0, s[2:3]
	s_mov_b64 s[2:3], 0xe000
	global_load_dwordx4 v[34:37], v[82:83], off sc0 sc1 nt
	v_lshl_add_u64 v[84:85], v[78:79], 0, s[2:3]
	s_mov_b64 s[2:3], 0x10000
	global_load_dwordx4 v[30:33], v[84:85], off sc0 sc1 nt
	v_lshl_add_u64 v[86:87], v[78:79], 0, s[2:3]
	s_mov_b64 s[2:3], 0x12000
	global_load_dwordx4 v[26:29], v[86:87], off sc0 sc1 nt
	v_lshl_add_u64 v[88:89], v[78:79], 0, s[2:3]
	s_mov_b64 s[2:3], 0x14000
	global_load_dwordx4 v[22:25], v[88:89], off sc0 sc1 nt
	v_lshl_add_u64 v[90:91], v[78:79], 0, s[2:3]
	s_mov_b64 s[2:3], 0x16000
	global_load_dwordx4 v[18:21], v[90:91], off sc0 sc1 nt
	v_lshl_add_u64 v[92:93], v[78:79], 0, s[2:3]
	s_mov_b64 s[2:3], 0x18000
	global_load_dwordx4 v[14:17], v[92:93], off sc0 sc1 nt
	v_lshl_add_u64 v[94:95], v[78:79], 0, s[2:3]
	global_load_dwordx4 v[10:13], v[94:95], off sc0 sc1 nt
	v_lshl_add_u64 v[96:97], v[78:79], 0, s[12:13]
	global_load_dwordx4 v[6:9], v[96:97], off sc0 sc1 nt
	v_lshl_add_u64 v[98:99], v[78:79], 0, s[14:15]
	global_load_dwordx4 v[2:5], v[98:99], off sc0 sc1 nt
	v_lshl_add_u64 v[100:101], v[78:79], 0, s[24:25]
	global_load_dwordx4 v[70:73], v[100:101], off sc0 sc1 nt
	v_lshl_add_u64 v[102:103], v[78:79], 0, s[26:27]
	global_load_dwordx4 v[66:69], v[102:103], off sc0 sc1 nt
	v_lshl_add_u64 v[104:105], v[78:79], 0, s[28:29]
	global_load_dwordx4 v[62:65], v[104:105], off sc0 sc1 nt
	v_lshl_add_u64 v[106:107], v[78:79], 0, s[34:35]
	global_load_dwordx4 v[58:61], v[106:107], off sc0 sc1 nt
	v_lshl_add_u64 v[108:109], v[78:79], 0, s[42:43]
	global_load_dwordx4 v[54:57], v[108:109], off sc0 sc1 nt
	v_lshl_add_u64 v[110:111], v[78:79], 0, s[46:47]
	global_load_dwordx4 v[50:53], v[110:111], off sc0 sc1 nt
	v_lshl_add_u64 v[112:113], v[78:79], 0, s[56:57]
	global_load_dwordx4 v[46:49], v[112:113], off sc0 sc1 nt
	v_lshl_add_u64 v[114:115], v[78:79], 0, s[58:59]
	global_load_dwordx4 v[42:45], v[114:115], off sc0 sc1 nt
	v_lshl_add_u64 v[78:79], v[78:79], 0, s[60:61]
	global_load_dwordx4 v[38:41], v[78:79], off sc0 sc1 nt
	v_lshl_add_u64 v[80:81], v[76:77], 0, s[6:7]
	s_waitcnt vmcnt(9)
	v_lshl_add_u64 v[116:117], v[80:81], 0, s[64:65]
	global_store_dwordx4 v[116:117], v[34:37], off nt
	s_nop 1
	v_lshl_add_u64 v[118:119], v[80:81], 0, s[66:67]
	global_store_dwordx4 v[118:119], v[30:33], off nt
	s_nop 1
	v_lshl_add_u64 v[120:121], v[80:81], 0, s[68:69]
	global_store_dwordx4 v[120:121], v[26:29], off nt
	s_nop 1
	v_lshl_add_u64 v[122:123], v[80:81], 0, s[0:1]
	global_store_dwordx4 v[122:123], v[22:25], off nt
	s_nop 1
	v_lshl_add_u64 v[124:125], v[80:81], 0, s[70:71]
	global_store_dwordx4 v[124:125], v[18:21], off nt
	s_nop 1
	v_lshl_add_u64 v[126:127], v[80:81], 0, s[72:73]
	global_store_dwordx4 v[126:127], v[14:17], off nt
	s_nop 1
	v_lshl_add_u64 v[128:129], v[80:81], 0, s[74:75]
	global_store_dwordx4 v[128:129], v[10:13], off nt
	s_nop 1
	v_lshl_add_u64 v[130:131], v[80:81], 0, s[76:77]
	global_store_dwordx4 v[130:131], v[6:9], off nt
	s_nop 1
	v_lshl_add_u64 v[132:133], v[80:81], 0, s[78:79]
	global_store_dwordx4 v[132:133], v[2:5], off nt
	s_nop 1
	s_waitcnt vmcnt(0)
	v_lshl_add_u64 v[134:135], v[80:81], 0, s[80:81]
	global_store_dwordx4 v[134:135], v[70:73], off nt
	s_nop 1
	v_lshl_add_u64 v[136:137], v[80:81], 0, s[82:83]
	global_store_dwordx4 v[136:137], v[66:69], off nt
	s_nop 1
	v_lshl_add_u64 v[138:139], v[80:81], 0, s[84:85]
	global_store_dwordx4 v[138:139], v[62:65], off nt
	s_nop 1
	v_lshl_add_u64 v[140:141], v[80:81], 0, s[86:87]
	global_store_dwordx4 v[140:141], v[58:61], off nt
	s_nop 1
	v_lshl_add_u64 v[142:143], v[80:81], 0, s[88:89]
	global_store_dwordx4 v[142:143], v[54:57], off nt
	s_nop 1
	v_lshl_add_u64 v[144:145], v[80:81], 0, s[90:91]
	global_store_dwordx4 v[144:145], v[50:53], off nt
	s_nop 1
	v_lshl_add_u64 v[146:147], v[80:81], 0, s[92:93]
	global_store_dwordx4 v[146:147], v[46:49], off nt
	s_nop 1
	v_lshl_add_u64 v[148:149], v[80:81], 0, s[94:95]
	global_store_dwordx4 v[148:149], v[42:45], off nt
	s_nop 1
	s_add_u32 s6, s6, 0x30000
	v_lshl_add_u64 v[80:81], v[80:81], 0, s[96:97]
	global_store_dwordx4 v[80:81], v[38:41], off nt
	s_nop 1
	s_addc_u32 s7, s7, 0
	s_cmp_lg_u32 s6, 0x120000
	s_cbranch_scc1 .LBB0_167
	s_waitcnt vmcnt(0)
	v_readlane_b32 s50, v248, 42
	v_readlane_b32 s51, v248, 43

.LBB0_339:
	v_lshl_add_u64 v[74:75], v[166:167], 0, s[8:9]
	s_mov_b64 s[0:1], 0xc000
	v_lshl_add_u64 v[76:77], v[74:75], 0, s[0:1]
	global_load_dwordx4 v[34:37], v[76:77], off sc0 sc1 nt
	s_mov_b64 s[0:1], 0xe000
	v_lshl_add_u64 v[76:77], v[74:75], 0, s[0:1]
	global_load_dwordx4 v[30:33], v[76:77], off sc0 sc1 nt
	s_mov_b64 s[0:1], 0x10000
	v_lshl_add_u64 v[76:77], v[74:75], 0, s[0:1]
	global_load_dwordx4 v[26:29], v[76:77], off sc0 sc1 nt
	s_mov_b64 s[0:1], 0x12000
	v_lshl_add_u64 v[76:77], v[74:75], 0, s[0:1]
	global_load_dwordx4 v[22:25], v[76:77], off sc0 sc1 nt
	s_mov_b64 s[0:1], 0x14000
	v_lshl_add_u64 v[76:77], v[74:75], 0, s[0:1]
	global_load_dwordx4 v[18:21], v[76:77], off sc0 sc1 nt
	s_mov_b64 s[0:1], 0x16000
	v_lshl_add_u64 v[76:77], v[74:75], 0, s[0:1]
	global_load_dwordx4 v[14:17], v[76:77], off sc0 sc1 nt
	s_mov_b64 s[0:1], 0x18000
	v_lshl_add_u64 v[76:77], v[74:75], 0, s[0:1]
	global_load_dwordx4 v[10:13], v[76:77], off sc0 sc1 nt
	s_mov_b64 s[0:1], 0x1a000
	v_lshl_add_u64 v[76:77], v[74:75], 0, s[0:1]
	global_load_dwordx4 v[6:9], v[76:77], off sc0 sc1 nt
	s_mov_b64 s[0:1], 0x1c000
	v_lshl_add_u64 v[76:77], v[74:75], 0, s[0:1]
	global_load_dwordx4 v[2:5], v[76:77], off sc0 sc1 nt
	s_mov_b64 s[0:1], 0x1e000
	v_lshl_add_u64 v[76:77], v[74:75], 0, s[0:1]
	global_load_dwordx4 v[70:73], v[76:77], off sc0 sc1 nt
	v_lshl_add_u64 v[76:77], v[74:75], 0, s[96:97]
	global_load_dwordx4 v[66:69], v[76:77], off sc0 sc1 nt
	s_mov_b64 s[0:1], 0x22000
	v_lshl_add_u64 v[76:77], v[74:75], 0, s[0:1]
	global_load_dwordx4 v[62:65], v[76:77], off sc0 sc1 nt
	v_lshl_add_u64 v[76:77], v[74:75], 0, s[98:99]
	global_load_dwordx4 v[58:61], v[76:77], off sc0 sc1 nt
	s_mov_b64 s[0:1], 0x26000
	v_lshl_add_u64 v[76:77], v[74:75], 0, s[0:1]
	global_load_dwordx4 v[54:57], v[76:77], off sc0 sc1 nt
	v_lshl_add_u64 v[76:77], v[74:75], 0, s[90:91]
	global_load_dwordx4 v[50:53], v[76:77], off sc0 sc1 nt
	s_mov_b64 s[0:1], 0x2a000
	v_lshl_add_u64 v[76:77], v[74:75], 0, s[0:1]
	global_load_dwordx4 v[46:49], v[76:77], off sc0 sc1 nt
	v_lshl_add_u64 v[76:77], v[74:75], 0, s[88:89]
	global_load_dwordx4 v[42:45], v[76:77], off sc0 sc1 nt
	s_mov_b64 s[0:1], 0x2e000
	v_lshl_add_u64 v[74:75], v[74:75], 0, s[0:1]
	global_load_dwordx4 v[38:41], v[74:75], off sc0 sc1 nt
	s_waitcnt vmcnt(9)
	v_lshl_add_u64 v[74:75], v[168:169], 0, s[8:9]
	s_mov_b64 s[0:1], 0xa31c000
	v_lshl_add_u64 v[76:77], v[74:75], 0, s[0:1]
	global_store_dwordx4 v[76:77], v[34:37], off nt
	s_nop 1
	s_mov_b64 s[0:1], 0xa31e000
	v_lshl_add_u64 v[76:77], v[74:75], 0, s[0:1]
	global_store_dwordx4 v[76:77], v[30:33], off nt
	s_nop 1
	s_mov_b64 s[0:1], 0xa320000
	v_lshl_add_u64 v[76:77], v[74:75], 0, s[0:1]
	global_store_dwordx4 v[76:77], v[26:29], off nt
	s_nop 1
	s_mov_b64 s[0:1], 0xa322000
	v_lshl_add_u64 v[76:77], v[74:75], 0, s[0:1]
	global_store_dwordx4 v[76:77], v[22:25], off nt
	s_nop 1
	s_mov_b64 s[0:1], 0xa324000
	v_lshl_add_u64 v[76:77], v[74:75], 0, s[0:1]
	global_store_dwordx4 v[76:77], v[18:21], off nt
	s_nop 1
	s_mov_b64 s[0:1], 0xa326000
	v_lshl_add_u64 v[76:77], v[74:75], 0, s[0:1]
	global_store_dwordx4 v[76:77], v[14:17], off nt
	s_nop 1
	s_mov_b64 s[0:1], 0xa328000
	v_lshl_add_u64 v[76:77], v[74:75], 0, s[0:1]
	global_store_dwordx4 v[76:77], v[10:13], off nt
	s_nop 1
	s_mov_b64 s[0:1], 0xa32a000
	v_lshl_add_u64 v[76:77], v[74:75], 0, s[0:1]
	global_store_dwordx4 v[76:77], v[6:9], off nt
	s_nop 1
	s_mov_b64 s[0:1], 0xa32c000
	v_lshl_add_u64 v[76:77], v[74:75], 0, s[0:1]
	global_store_dwordx4 v[76:77], v[2:5], off nt
	s_nop 1
	s_waitcnt vmcnt(0)
	s_mov_b64 s[0:1], 0xa32e000
	v_lshl_add_u64 v[76:77], v[74:75], 0, s[0:1]
	global_store_dwordx4 v[76:77], v[70:73], off nt
	s_nop 1
	s_mov_b64 s[0:1], 0xa330000
	v_lshl_add_u64 v[76:77], v[74:75], 0, s[0:1]
	global_store_dwordx4 v[76:77], v[66:69], off nt
	s_nop 1
	s_mov_b64 s[0:1], 0xa332000
	v_lshl_add_u64 v[76:77], v[74:75], 0, s[0:1]
	global_store_dwordx4 v[76:77], v[62:65], off nt
	s_nop 1
	s_mov_b64 s[0:1], 0xa334000
	v_lshl_add_u64 v[76:77], v[74:75], 0, s[0:1]
	global_store_dwordx4 v[76:77], v[58:61], off nt
	s_nop 1
	s_mov_b64 s[0:1], 0xa336000
	v_lshl_add_u64 v[76:77], v[74:75], 0, s[0:1]
	global_store_dwordx4 v[76:77], v[54:57], off nt
	s_nop 1
	s_mov_b64 s[0:1], 0xa338000
	v_lshl_add_u64 v[76:77], v[74:75], 0, s[0:1]
	global_store_dwordx4 v[76:77], v[50:53], off nt
	s_nop 1
	s_mov_b64 s[0:1], 0xa33a000
	v_lshl_add_u64 v[76:77], v[74:75], 0, s[0:1]
	global_store_dwordx4 v[76:77], v[46:49], off nt
	s_nop 1
	s_mov_b64 s[0:1], 0xa33c000
	v_lshl_add_u64 v[76:77], v[74:75], 0, s[0:1]
	global_store_dwordx4 v[76:77], v[42:45], off nt
	s_nop 1
	s_mov_b64 s[0:1], 0xa33e000
	v_lshl_add_u64 v[74:75], v[74:75], 0, s[0:1]
	global_store_dwordx4 v[74:75], v[38:41], off nt
	s_nop 1
	s_add_u32 s8, s8, 0x30000
	s_addc_u32 s9, s9, 0
	s_cmp_lg_u32 s8, 0x120000
	s_cbranch_scc1 .LBB0_339
	s_waitcnt vmcnt(0)
	s_mov_b64 s[20:21], -1
	s_branch .LBB0_172

.LBB0_366:
	v_lshl_add_u64 v[78:79], v[74:75], 0, s[6:7]
	s_mov_b64 s[0:1], 0xc000
	v_lshl_add_u64 v[80:81], v[78:79], 0, s[0:1]
	global_load_dwordx4 v[34:37], v[80:81], off sc0 sc1 nt
	s_mov_b64 s[0:1], 0xe000
	v_lshl_add_u64 v[80:81], v[78:79], 0, s[0:1]
	global_load_dwordx4 v[30:33], v[80:81], off sc0 sc1 nt
	s_mov_b64 s[0:1], 0x10000
	v_lshl_add_u64 v[80:81], v[78:79], 0, s[0:1]
	global_load_dwordx4 v[26:29], v[80:81], off sc0 sc1 nt
	v_lshl_add_u64 v[80:81], v[78:79], 0, s[8:9]
	global_load_dwordx4 v[22:25], v[80:81], off sc0 sc1 nt
	v_lshl_add_u64 v[80:81], v[78:79], 0, s[10:11]
	global_load_dwordx4 v[18:21], v[80:81], off sc0 sc1 nt
	v_lshl_add_u64 v[80:81], v[78:79], 0, s[12:13]
	global_load_dwordx4 v[14:17], v[80:81], off sc0 sc1 nt
	v_lshl_add_u64 v[80:81], v[78:79], 0, s[24:25]
	global_load_dwordx4 v[10:13], v[80:81], off sc0 sc1 nt
	v_lshl_add_u64 v[80:81], v[78:79], 0, s[26:27]
	global_load_dwordx4 v[6:9], v[80:81], off sc0 sc1 nt
	v_lshl_add_u64 v[80:81], v[78:79], 0, s[28:29]
	global_load_dwordx4 v[2:5], v[80:81], off sc0 sc1 nt
	v_lshl_add_u64 v[80:81], v[78:79], 0, s[34:35]
	global_load_dwordx4 v[70:73], v[80:81], off sc0 sc1 nt
	v_lshl_add_u64 v[80:81], v[78:79], 0, s[42:43]
	global_load_dwordx4 v[66:69], v[80:81], off sc0 sc1 nt
	v_lshl_add_u64 v[80:81], v[78:79], 0, s[46:47]
	global_load_dwordx4 v[62:65], v[80:81], off sc0 sc1 nt
	v_lshl_add_u64 v[80:81], v[78:79], 0, s[56:57]
	global_load_dwordx4 v[58:61], v[80:81], off sc0 sc1 nt
	v_lshl_add_u64 v[80:81], v[78:79], 0, s[58:59]
	global_load_dwordx4 v[54:57], v[80:81], off sc0 sc1 nt
	v_lshl_add_u64 v[80:81], v[78:79], 0, s[60:61]
	global_load_dwordx4 v[50:53], v[80:81], off sc0 sc1 nt
	v_lshl_add_u64 v[80:81], v[78:79], 0, s[62:63]
	global_load_dwordx4 v[46:49], v[80:81], off sc0 sc1 nt
	v_lshl_add_u64 v[80:81], v[78:79], 0, s[64:65]
	global_load_dwordx4 v[42:45], v[80:81], off sc0 sc1 nt
	v_lshl_add_u64 v[78:79], v[78:79], 0, s[66:67]
	global_load_dwordx4 v[38:41], v[78:79], off sc0 sc1 nt
	s_waitcnt vmcnt(9)
	v_lshl_add_u64 v[78:79], v[76:77], 0, s[6:7]
	v_lshl_add_u64 v[80:81], v[78:79], 0, s[68:69]
	global_store_dwordx4 v[80:81], v[34:37], off nt
	s_nop 1
	v_lshl_add_u64 v[80:81], v[78:79], 0, s[70:71]
	global_store_dwordx4 v[80:81], v[30:33], off nt
	s_nop 1
	v_lshl_add_u64 v[80:81], v[78:79], 0, s[72:73]
	global_store_dwordx4 v[80:81], v[26:29], off nt
	s_nop 1
	v_lshl_add_u64 v[80:81], v[78:79], 0, s[74:75]
	global_store_dwordx4 v[80:81], v[22:25], off nt
	s_nop 1
	v_lshl_add_u64 v[80:81], v[78:79], 0, s[76:77]
	global_store_dwordx4 v[80:81], v[18:21], off nt
	s_nop 1
	v_lshl_add_u64 v[80:81], v[78:79], 0, s[78:79]
	global_store_dwordx4 v[80:81], v[14:17], off nt
	s_nop 1
	v_lshl_add_u64 v[80:81], v[78:79], 0, s[80:81]
	global_store_dwordx4 v[80:81], v[10:13], off nt
	s_nop 1
	v_lshl_add_u64 v[80:81], v[78:79], 0, s[82:83]
	global_store_dwordx4 v[80:81], v[6:9], off nt
	s_nop 1
	v_lshl_add_u64 v[80:81], v[78:79], 0, s[84:85]
	global_store_dwordx4 v[80:81], v[2:5], off nt
	s_nop 1
	s_waitcnt vmcnt(0)
	v_lshl_add_u64 v[80:81], v[78:79], 0, s[86:87]
	global_store_dwordx4 v[80:81], v[70:73], off nt
	s_nop 1
	v_lshl_add_u64 v[80:81], v[78:79], 0, s[88:89]
	global_store_dwordx4 v[80:81], v[66:69], off nt
	s_nop 1
	v_lshl_add_u64 v[80:81], v[78:79], 0, s[90:91]
	global_store_dwordx4 v[80:81], v[62:65], off nt
	s_nop 1
	v_lshl_add_u64 v[80:81], v[78:79], 0, s[92:93]
	global_store_dwordx4 v[80:81], v[58:61], off nt
	s_nop 1
	v_lshl_add_u64 v[80:81], v[78:79], 0, s[94:95]
	global_store_dwordx4 v[80:81], v[54:57], off nt
	s_nop 1
	v_lshl_add_u64 v[80:81], v[78:79], 0, s[96:97]
	global_store_dwordx4 v[80:81], v[50:53], off nt
	s_nop 1
	v_lshl_add_u64 v[80:81], v[78:79], 0, s[98:99]
	global_store_dwordx4 v[80:81], v[46:49], off nt
	s_nop 1
	v_lshl_add_u64 v[80:81], v[78:79], 0, vcc
	global_store_dwordx4 v[80:81], v[42:45], off nt
	s_nop 1
	v_lshl_add_u64 v[78:79], v[78:79], 0, s[14:15]
	global_store_dwordx4 v[78:79], v[38:41], off nt
	s_nop 1
	s_add_u32 s6, s6, 0x30000
	s_addc_u32 s7, s7, 0
	s_cmp_lg_u32 s6, 0x120000
	s_cbranch_scc1 .LBB0_366
	s_waitcnt vmcnt(0)

.LBB0_375:
	s_load_dwordx4 s[16:19], s[52:53], 0x80
	s_waitcnt lgkmcnt(0)
	global_load_dword v8, v1, s[16:17] offset:520 sc1
	s_waitcnt vmcnt(0)
	v_cmp_lt_u32_e32 vcc, s4, v8
	v_mov_b32_e32 v8, 0x600
	s_cbranch_vccnz .LBB0_379
	s_mov_b64 s[36:37], exec
	v_mbcnt_lo_u32_b32 v8, s36, 0
	v_mbcnt_hi_u32_b32 v8, s37, v8
	v_cmp_eq_u32_e32 vcc, 0, v8
	s_and_saveexec_b64 s[34:35], vcc
	s_cbranch_execz .LBB0_378
	s_load_dwordx4 s[16:19], s[52:53], 0x80
	s_bcnt1_i32_b64 s9, s[36:37]
	v_mov_b32_e32 v9, s9
	s_waitcnt lgkmcnt(0)
	global_atomic_add v9, v1, v9, s[16:17] offset:768 sc0

.LBB0_380:
	s_or_b64 exec, exec, s[10:11]
	s_waitcnt lgkmcnt(0)
	s_barrier
	ds_read_b32 v8, v6
	s_mov_b64 s[34:35], -1
	s_mov_b64 s[10:11], -1
	s_waitcnt lgkmcnt(0)
	v_readfirstlane_b32 s9, v8
	s_cmpk_gt_i32 s9, 0x5ff
	s_cbranch_scc1 .LBB0_369
	s_mul_hi_i32 s10, s9, 0x2aaaaaab
	s_lshr_b32 s11, s10, 31
	s_add_i32 s16, s10, s11
	s_mul_i32 s10, s16, 6
	s_sub_i32 s9, s9, s10
	s_ashr_i32 s17, s16, 3
	s_add_i32 s9, s9, 6
	v_mad_i64_i32 v[8:9], s[10:11], s17, v7, v[2:3]
	s_and_b32 s16, s16, 7
	v_mad_i64_i32 v[80:81], s[10:11], s17, v7, v[4:5]
	s_mul_i32 s16, s16, 0x24000
	s_mul_hi_u32 s11, s9, 0x3000
	s_mulk_i32 s9, 0x3000
	s_add_u32 s10, s9, s16
	s_addc_u32 s11, s11, 0
	s_lshl_b64 s[16:17], s[10:11], 4
	s_mov_b32 s10, s8
	s_mov_b32 s11, s8
	v_lshl_add_u64 v[48:49], v[8:9], 0, s[0:1]
	s_mov_b32 s9, s8
	v_mov_b64_e32 v[14:15], s[10:11]
	s_waitcnt vmcnt(0)
	v_lshl_add_u64 v[44:45], v[48:49], 0, s[16:17]
	v_mov_b64_e32 v[12:13], s[8:9]
	v_mov_b64_e32 v[18:19], s[10:11]
	global_load_dwordx4 v[12:15], v[44:45], off sc0 sc1 nt
	v_lshl_add_u64 v[20:21], v[44:45], 0, s[2:3]
	v_mov_b64_e32 v[16:17], s[8:9]
	global_load_dwordx4 v[16:19], v[20:21], off sc0 sc1 nt
	v_mov_b64_e32 v[22:23], s[10:11]
	v_lshl_add_u64 v[24:25], v[44:45], 0, s[6:7]
	v_mov_b64_e32 v[20:21], s[8:9]
	global_load_dwordx4 v[20:23], v[24:25], off sc0 sc1 nt
	v_mov_b64_e32 v[26:27], s[10:11]
	v_lshl_add_u64 v[28:29], v[44:45], 0, s[12:13]
	v_mov_b64_e32 v[24:25], s[8:9]
	global_load_dwordx4 v[24:27], v[28:29], off sc0 sc1 nt
	v_mov_b64_e32 v[30:31], s[10:11]
	v_lshl_add_u64 v[32:33], v[44:45], 0, s[14:15]
	v_mov_b64_e32 v[28:29], s[8:9]
	global_load_dwordx4 v[28:31], v[32:33], off sc0 sc1 nt
	v_mov_b64_e32 v[34:35], s[10:11]
	v_lshl_add_u64 v[36:37], v[44:45], 0, s[24:25]
	v_mov_b64_e32 v[32:33], s[8:9]
	global_load_dwordx4 v[32:35], v[36:37], off sc0 sc1 nt
	v_mov_b64_e32 v[38:39], s[10:11]
	v_lshl_add_u64 v[40:41], v[44:45], 0, s[0:1]
	v_mov_b64_e32 v[36:37], s[8:9]
	global_load_dwordx4 v[36:39], v[40:41], off sc0 sc1 nt
	v_mov_b64_e32 v[42:43], s[10:11]
	v_lshl_add_u64 v[46:47], v[44:45], 0, s[26:27]
	v_mov_b64_e32 v[40:41], s[8:9]
	v_mov_b64_e32 v[8:9], s[8:9]
	global_load_dwordx4 v[40:43], v[46:47], off sc0 sc1 nt
	v_lshl_add_u64 v[50:51], v[44:45], 0, s[28:29]
	v_mov_b64_e32 v[46:47], s[10:11]
	v_mov_b64_e32 v[10:11], s[10:11]
	v_mov_b64_e32 v[44:45], s[8:9]
	s_add_u32 s10, s16, 0x12000
	s_addc_u32 s11, s17, 0
	global_load_dwordx4 v[44:47], v[50:51], off sc0 sc1 nt
	v_lshl_add_u64 v[82:83], v[48:49], 0, s[10:11]
	v_mov_b64_e32 v[50:51], v[10:11]
	v_mov_b64_e32 v[48:49], v[8:9]
	v_mov_b64_e32 v[54:55], v[10:11]
	global_load_dwordx4 v[48:51], v[82:83], off sc0 sc1 nt
	v_lshl_add_u64 v[56:57], v[82:83], 0, s[2:3]
	v_mov_b64_e32 v[52:53], v[8:9]
	global_load_dwordx4 v[52:55], v[56:57], off sc0 sc1 nt
	v_mov_b64_e32 v[58:59], v[10:11]
	v_lshl_add_u64 v[60:61], v[82:83], 0, s[6:7]
	v_mov_b64_e32 v[56:57], v[8:9]
	global_load_dwordx4 v[56:59], v[60:61], off sc0 sc1 nt
	v_mov_b64_e32 v[62:63], v[10:11]
	v_lshl_add_u64 v[64:65], v[82:83], 0, s[12:13]
	v_mov_b64_e32 v[60:61], v[8:9]
	global_load_dwordx4 v[60:63], v[64:65], off sc0 sc1 nt
	v_mov_b64_e32 v[66:67], v[10:11]
	v_lshl_add_u64 v[68:69], v[82:83], 0, s[14:15]
	v_mov_b64_e32 v[64:65], v[8:9]
	global_load_dwordx4 v[64:67], v[68:69], off sc0 sc1 nt
	v_mov_b64_e32 v[70:71], v[10:11]
	v_lshl_add_u64 v[72:73], v[82:83], 0, s[24:25]
	v_mov_b64_e32 v[68:69], v[8:9]
	global_load_dwordx4 v[68:71], v[72:73], off sc0 sc1 nt
	v_mov_b64_e32 v[74:75], v[10:11]
	v_lshl_add_u64 v[76:77], v[82:83], 0, s[0:1]
	v_mov_b64_e32 v[72:73], v[8:9]
	global_load_dwordx4 v[72:75], v[76:77], off sc0 sc1 nt
	v_mov_b64_e32 v[78:79], v[10:11]
	v_mov_b64_e32 v[76:77], v[8:9]
	v_lshl_add_u64 v[84:85], v[82:83], 0, s[26:27]
	global_load_dwordx4 v[76:79], v[84:85], off sc0 sc1 nt
	v_lshl_add_u64 v[82:83], v[82:83], 0, s[28:29]
	global_load_dwordx4 v[8:11], v[82:83], off sc0 sc1 nt
	s_waitcnt vmcnt(9)
	v_lshl_add_u64 v[82:83], v[80:81], 0, s[16:17]
	global_store_dwordx4 v[82:83], v[12:15], off nt
	s_nop 1
	v_lshl_add_u64 v[12:13], v[82:83], 0, s[2:3]
	global_store_dwordx4 v[12:13], v[16:19], off nt
	s_nop 1
	v_lshl_add_u64 v[12:13], v[82:83], 0, s[6:7]
	global_store_dwordx4 v[12:13], v[20:23], off nt
	s_nop 1
	v_lshl_add_u64 v[12:13], v[82:83], 0, s[12:13]
	global_store_dwordx4 v[12:13], v[24:27], off nt
	s_nop 1
	v_lshl_add_u64 v[12:13], v[82:83], 0, s[14:15]
	global_store_dwordx4 v[12:13], v[28:31], off nt
	s_nop 1
	v_lshl_add_u64 v[12:13], v[82:83], 0, s[24:25]
	global_store_dwordx4 v[12:13], v[32:35], off nt
	s_nop 1
	v_lshl_add_u64 v[12:13], v[82:83], 0, s[0:1]
	global_store_dwordx4 v[12:13], v[36:39], off nt
	s_nop 1
	v_lshl_add_u64 v[12:13], v[82:83], 0, s[26:27]
	global_store_dwordx4 v[12:13], v[40:43], off nt
	s_nop 1
	v_lshl_add_u64 v[12:13], v[82:83], 0, s[28:29]
	global_store_dwordx4 v[12:13], v[44:47], off nt
	s_nop 1
	s_waitcnt vmcnt(0)
	v_lshl_add_u64 v[12:13], v[80:81], 0, s[10:11]
	global_store_dwordx4 v[12:13], v[48:51], off nt
	s_nop 1
	v_lshl_add_u64 v[14:15], v[12:13], 0, s[2:3]
	global_store_dwordx4 v[14:15], v[52:55], off nt
	s_nop 1
	v_lshl_add_u64 v[14:15], v[12:13], 0, s[6:7]
	global_store_dwordx4 v[14:15], v[56:59], off nt
	s_nop 1
	v_lshl_add_u64 v[14:15], v[12:13], 0, s[12:13]
	global_store_dwordx4 v[14:15], v[60:63], off nt
	s_nop 1
	v_lshl_add_u64 v[14:15], v[12:13], 0, s[14:15]
	global_store_dwordx4 v[14:15], v[64:67], off nt
	s_nop 1
	v_lshl_add_u64 v[14:15], v[12:13], 0, s[24:25]
	global_store_dwordx4 v[14:15], v[68:71], off nt
	s_nop 1
	v_lshl_add_u64 v[14:15], v[12:13], 0, s[0:1]
	global_store_dwordx4 v[14:15], v[72:75], off nt
	s_nop 1
	v_lshl_add_u64 v[14:15], v[12:13], 0, s[26:27]
	global_store_dwordx4 v[14:15], v[76:79], off nt
	s_nop 1
	v_lshl_add_u64 v[12:13], v[12:13], 0, s[28:29]
	global_store_dwordx4 v[12:13], v[8:11], off nt
	s_nop 1
	s_waitcnt vmcnt(0)
	s_mov_b64 s[10:11], 0
	s_branch .LBB0_369

.LBB0_436:
	s_and_b32 s100, s33, 7
	s_mov_b32 s101, 0
	s_load_dwordx4 s[28:31], s[52:53], 0x80
	s_waitcnt lgkmcnt(0)
	s_cmp_lt_i32 s30, 3
	s_cselect_b64 s[0:1], -1, 0
	s_and_b64 s[0:1], s[0:1], s[6:7]
	s_andn2_b64 vcc, exec, s[0:1]
	s_cbranch_vccnz .LBB0_610
	s_load_dwordx16 s[12:27], s[52:53], 0x0
	v_writelane_b32 v248, s0, 48
	v_mbcnt_lo_u32_b32 v3, -1, 0
	s_mov_b32 s11, 0x27000
	v_writelane_b32 v248, s1, 49
	s_waitcnt lgkmcnt(0)
	s_mov_b64 s[6:7], s[18:19]
	s_and_b32 s9, s7, 0xffff
	v_writelane_b32 v248, s33, 46
	s_add_u32 s0, s28, 0x2900000
	v_writelane_b32 v248, s0, 47
	s_addc_u32 s0, s29, 0
	v_writelane_b32 v248, s0, 44
	s_add_i32 s2, 0, 0x23200
	s_brev_b32 s10, -2
	s_mov_b32 s8, s18
	s_mov_b64 s[0:1], -1
	s_mov_b32 s21, 0
	v_mov_b32_e32 v2, 0
	v_writelane_b32 v248, s2, 38
	v_mov_b32_e32 v1, s2
	s_add_i32 s51, 0, 0x20000
	s_movk_i32 s33, 0x1000
	s_movk_i32 s50, 0x2000
	s_add_i32 s2, 0, 0x20800
	s_movk_i32 s19, 0x3000
	s_add_i32 s46, 0, 0x10000
	s_movk_i32 s6, 0x4000
	s_movk_i32 s17, 0x6000
	s_mov_b32 s31, 0x41000000
	s_movk_i32 s22, 0x5000
	s_movk_i32 s30, 0x7000
	v_mov_b32_e32 v204, 0x358637bd
	s_mov_b32 s18, 0xf800000
	v_mov_b32_e32 v205, 0x260
	v_mov_b32_e32 v196, 0xe0ad78ec
	v_mbcnt_hi_u32_b32 v206, -1, v3
	v_mov_b32_e32 v207, 3
	v_mov_b32_e32 v208, 2
	v_mov_b32_e32 v209, 1
	s_mov_b64 s[26:27], 0x100
	s_mov_b64 s[28:29], 0x1800
	s_mov_b64 s[34:35], 0x1900
	v_writelane_b32 v248, s2, 50
	s_branch .LBB0_440

.LBB0_445:
	s_load_dwordx4 s[4:7], s[52:53], 0x80
	s_waitcnt lgkmcnt(0)
.Lxq_try:
	s_cmpk_gt_u32 s101, 7
	s_cbranch_scc1 .Lxq_none
	s_add_i32 s6, s100, s101
	s_and_b32 s6, s6, 7
	s_lshl_b32 s7, s6, 8
	s_addk_i32 s7, 0x400
	v_mov_b32_e32 v3, s7
	v_mov_b32_e32 v4, 1
	s_nop 0
	global_atomic_add v4, v3, v4, s[4:5] sc0
	s_waitcnt vmcnt(0)
	v_readfirstlane_b32 s7, v4
	s_movk_i32 s0, 0x70
	s_cmpk_lt_u32 s6, 2
	s_addc_u32 s0, s0, 0
	s_cmp_lt_u32 s7, s0
	s_cbranch_scc1 .Lxq_have
	s_add_i32 s101, s101, 1
	s_branch .Lxq_try
.Lxq_have:
	s_cmpk_lt_u32 s7, 16
	s_cbranch_scc0 .Lxq_b
	s_lshl_b32 s7, s7, 3
	s_add_i32 s6, s6, s7
	s_branch .Lq_done
.Lxq_b:
	s_cmpk_lt_u32 s7, 40
	s_cbranch_scc0 .Lxq_c
	s_sub_i32 s7, s7, 16
	s_lshr_b32 s0, s7, 1
	s_bitcmp1_b32 s7, 0
	s_cbranch_scc1 .Lxq_sa
	s_branch .Lxq_pa
.Lxq_c:
	s_cmpk_lt_u32 s7, 94
	s_cbranch_scc0 .Lxq_d
	s_sub_i32 s7, s7, 40
	s_mul_i32 s0, s7, 0xab
	s_lshr_b32 s0, s0, 9
	s_mul_i32 s1, s0, 3
	s_sub_i32 s7, s7, s1
	s_cmpk_eq_u32 s7, 2
	s_cbranch_scc1 .Lxq_c_pa
	s_lshl_b32 s0, s0, 1
	s_add_i32 s0, s0, s7
	s_addk_i32 s0, 12
	s_branch .Lxq_sa
.Lxq_c_pa:
	s_addk_i32 s0, 12
	s_branch .Lxq_pa
.Lxq_d:
	s_cmpk_lt_u32 s7, 112
	s_cbranch_scc0 .Lxq_e
	s_sub_i32 s0, s7, 64
	s_branch .Lxq_pa
.Lxq_e:
	s_addk_i32 s6, 128
	s_branch .Lq_done
.Lxq_sa:
	s_lshl_b32 s0, s0, 3
	s_add_i32 s6, s6, s0
	s_addk_i32 s6, 0x202
	s_branch .Lq_done
.Lxq_pa:
	s_mul_i32 s1, s0, 43
	s_lshr_b32 s1, s1, 8
	s_mul_i32 s7, s1, 6
	s_sub_i32 s0, s0, s7
	s_mul_i32 s1, s1, 48
	s_lshl_b32 s0, s0, 3
	s_add_i32 s6, s6, s0
	s_add_i32 s6, s6, s1
	s_addk_i32 s6, 0x82
	s_branch .Lq_done
.Lxq_none:
	s_movk_i32 s6, 0x7fff
.Lq_done:
	v_mov_b32_e32 v3, s6
	v_readlane_b32 s0, v248, 38
	s_movk_i32 s6, 0x4000
	s_nop 0
	v_mov_b32_e32 v4, s0
	ds_write_b32 v4, v3
.LBB0_448:
	s_or_b64 exec, exec, s[2:3]
	s_waitcnt lgkmcnt(0)
	s_barrier
	ds_read_b32 v3, v1
	s_mov_b64 s[2:3], -1
	s_waitcnt lgkmcnt(0)
	s_barrier
	v_readfirstlane_b32 s4, v3
	s_cmpk_gt_i32 s4, 0x381
	s_cbranch_scc1 .LBB0_439
	s_cmpk_gt_i32 s4, 0x81
	s_mov_b64 s[0:1], -1
	s_cbranch_scc0 .LBB0_519
	s_cmpk_lt_u32 s4, 0x202
	s_cbranch_scc0 .Lq_is_sa
	s_add_i32 s5, s4, 0xffffff7e
	s_mov_b32 s2, -1
	s_branch .LBB0_483
.Lq_is_sa:
	s_add_i32 s2, s4, 0xfffffdfe
	s_mov_b32 s5, -1

.LBB0_479:
	s_or_b64 exec, exec, s[0:1]
	v_add_f32_e32 v168, v168, v169
	s_waitcnt lgkmcnt(7)
	v_add_f32_e32 v168, v140, v168
	v_add_f32_e32 v140, v170, v171
	v_add_f32_e32 v141, v141, v140
	v_add_f32_e32 v140, v174, v175
	s_waitcnt lgkmcnt(6)
	v_add_f32_e32 v169, v128, v140
	v_add_f32_e32 v128, v178, v179
	v_add_f32_e32 v129, v129, v128
	v_add_f32_e32 v128, v180, v181
	s_waitcnt lgkmcnt(5)
	v_add_f32_e32 v128, v114, v128
	v_add_f32_e32 v114, v182, v183
	v_add_f32_e32 v170, v115, v114
	v_add_f32_e32 v114, v184, v185
	s_waitcnt lgkmcnt(4)
	v_add_f32_e32 v171, v112, v114
	v_add_f32_e32 v112, v186, v187
	v_add_f32_e32 v172, v113, v112
	v_add_f32_e32 v112, v188, v189
	s_waitcnt lgkmcnt(3)
	v_add_f32_e32 v113, v148, v112
	v_add_f32_e32 v112, v190, v191
	v_add_f32_e32 v148, v149, v112
	v_add_f32_e32 v112, v192, v193
	s_waitcnt lgkmcnt(2)
	v_add_f32_e32 v149, v146, v112
	v_add_f32_e32 v112, v197, v198
	v_add_f32_e32 v173, v147, v112
	v_add_f32_e32 v112, v199, v200
	s_waitcnt lgkmcnt(1)
	v_add_f32_e32 v115, v144, v112
	v_add_f32_e32 v112, v201, v202
	v_add_f32_e32 v147, v145, v112
	v_add_f32_e32 v112, v203, v210
	s_waitcnt lgkmcnt(0)
	v_add_f32_e32 v174, v142, v112
	v_add_f32_e32 v112, v211, v212
	v_add_f32_e32 v175, v143, v112
	v_max3_f32 v112, v168, v128, v113
	v_max3_f32 v140, v167, v112, v115
	v_sub_f32_e32 v112, v167, v140
	v_exp_f32_e32 v112, v112
	v_sub_f32_e32 v114, v168, v140
	v_exp_f32_e32 v114, v114
	v_sub_f32_e32 v113, v113, v140
	v_exp_f32_e32 v144, v113
	v_sub_f32_e32 v113, v115, v140
	v_sub_f32_e32 v128, v128, v140
	v_exp_f32_e32 v146, v113
	v_pk_mul_f32 v[32:33], v[32:33], v[112:113] op_sel_hi:[1,0]
	v_pk_mul_f32 v[34:35], v[34:35], v[112:113] op_sel_hi:[1,0]
	v_pk_mul_f32 v[28:29], v[28:29], v[112:113] op_sel_hi:[1,0]
	v_pk_mul_f32 v[30:31], v[30:31], v[112:113] op_sel_hi:[1,0]
	v_max3_f32 v113, v141, v170, v148
	v_exp_f32_e32 v142, v128
	v_max3_f32 v128, v166, v113, v147
	v_pk_fma_f32 v[32:33], v[44:45], v[114:115], v[32:33] op_sel_hi:[1,0,1]
	v_pk_fma_f32 v[34:35], v[46:47], v[114:115], v[34:35] op_sel_hi:[1,0,1]
	v_pk_fma_f32 v[28:29], v[48:49], v[114:115], v[28:29] op_sel_hi:[1,0,1]
	v_pk_fma_f32 v[30:31], v[50:51], v[114:115], v[30:31] op_sel_hi:[1,0,1]
	v_sub_f32_e32 v113, v166, v128
	v_sub_f32_e32 v115, v141, v128
	v_exp_f32_e32 v113, v113
	v_exp_f32_e32 v115, v115
	v_sub_f32_e32 v141, v170, v128
	v_pk_fma_f32 v[32:33], v[60:61], v[142:143], v[32:33] op_sel_hi:[1,0,1]
	v_pk_fma_f32 v[34:35], v[62:63], v[142:143], v[34:35] op_sel_hi:[1,0,1]
	v_pk_fma_f32 v[28:29], v[64:65], v[142:143], v[28:29] op_sel_hi:[1,0,1]
	v_pk_fma_f32 v[30:31], v[66:67], v[142:143], v[30:31] op_sel_hi:[1,0,1]
	v_exp_f32_e32 v143, v141
	v_sub_f32_e32 v141, v148, v128
	v_pk_fma_f32 v[32:33], v[76:77], v[144:145], v[32:33] op_sel_hi:[1,0,1]
	v_pk_fma_f32 v[34:35], v[78:79], v[144:145], v[34:35] op_sel_hi:[1,0,1]
	v_pk_fma_f32 v[28:29], v[80:81], v[144:145], v[28:29] op_sel_hi:[1,0,1]
	v_pk_fma_f32 v[30:31], v[82:83], v[144:145], v[30:31] op_sel_hi:[1,0,1]
	v_exp_f32_e32 v145, v141
	v_sub_f32_e32 v141, v147, v128
	v_pk_fma_f32 v[104:105], v[104:105], v[112:113], v[114:115]
	v_mov_b32_e32 v112, v113
	v_pk_fma_f32 v[32:33], v[92:93], v[146:147], v[32:33] op_sel_hi:[1,0,1]
	v_pk_fma_f32 v[34:35], v[94:95], v[146:147], v[34:35] op_sel_hi:[1,0,1]
	v_pk_fma_f32 v[28:29], v[96:97], v[146:147], v[28:29] op_sel_hi:[1,0,1]
	v_pk_fma_f32 v[30:31], v[98:99], v[146:147], v[30:31] op_sel_hi:[1,0,1]
	v_exp_f32_e32 v147, v141
	v_pk_mul_f32 v[24:25], v[24:25], v[112:113] op_sel_hi:[1,0]
	v_mov_b32_e32 v114, v115
	v_pk_mul_f32 v[26:27], v[26:27], v[112:113] op_sel_hi:[1,0]
	v_pk_mul_f32 v[20:21], v[20:21], v[112:113] op_sel_hi:[1,0]
	v_pk_mul_f32 v[22:23], v[22:23], v[112:113] op_sel_hi:[1,0]
	v_max3_f32 v112, v169, v171, v149
	v_pk_fma_f32 v[24:25], v[44:45], v[114:115], v[24:25] op_sel_hi:[1,0,1]
	v_pk_fma_f32 v[26:27], v[46:47], v[114:115], v[26:27] op_sel_hi:[1,0,1]
	v_pk_fma_f32 v[20:21], v[48:49], v[114:115], v[20:21] op_sel_hi:[1,0,1]
	v_pk_fma_f32 v[22:23], v[50:51], v[114:115], v[22:23] op_sel_hi:[1,0,1]
	v_max3_f32 v114, v165, v112, v174
	v_pk_add_f32 v[104:105], v[142:143], v[104:105]
	v_mov_b32_e32 v142, v143
	v_sub_f32_e32 v112, v165, v114
	v_pk_add_f32 v[104:105], v[144:145], v[104:105]
	v_pk_fma_f32 v[24:25], v[60:61], v[142:143], v[24:25] op_sel_hi:[1,0,1]
	v_mov_b32_e32 v144, v145
	v_pk_fma_f32 v[26:27], v[62:63], v[142:143], v[26:27] op_sel_hi:[1,0,1]
	v_pk_fma_f32 v[20:21], v[64:65], v[142:143], v[20:21] op_sel_hi:[1,0,1]
	v_pk_fma_f32 v[22:23], v[66:67], v[142:143], v[22:23] op_sel_hi:[1,0,1]
	v_exp_f32_e32 v142, v112
	v_sub_f32_e32 v112, v169, v114
	v_pk_add_f32 v[104:105], v[146:147], v[104:105]
	v_pk_fma_f32 v[24:25], v[76:77], v[144:145], v[24:25] op_sel_hi:[1,0,1]
	v_mov_b32_e32 v146, v147
	v_pk_fma_f32 v[26:27], v[78:79], v[144:145], v[26:27] op_sel_hi:[1,0,1]
	v_pk_fma_f32 v[20:21], v[80:81], v[144:145], v[20:21] op_sel_hi:[1,0,1]
	v_pk_fma_f32 v[22:23], v[82:83], v[144:145], v[22:23] op_sel_hi:[1,0,1]
	v_exp_f32_e32 v144, v112
	v_sub_f32_e32 v112, v171, v114
	v_pk_fma_f32 v[24:25], v[92:93], v[146:147], v[24:25] op_sel_hi:[1,0,1]
	v_pk_fma_f32 v[26:27], v[94:95], v[146:147], v[26:27] op_sel_hi:[1,0,1]
	v_pk_fma_f32 v[20:21], v[96:97], v[146:147], v[20:21] op_sel_hi:[1,0,1]
	v_pk_fma_f32 v[22:23], v[98:99], v[146:147], v[22:23] op_sel_hi:[1,0,1]
	v_exp_f32_e32 v146, v112
	v_sub_f32_e32 v112, v149, v114
	v_exp_f32_e32 v148, v112
	v_sub_f32_e32 v112, v174, v114
	v_exp_f32_e32 v166, v112
	v_max3_f32 v112, v129, v172, v173
	v_max3_f32 v112, v164, v112, v175
	v_sub_f32_e32 v113, v164, v112
	v_pk_mul_f32 v[16:17], v[16:17], v[142:143] op_sel_hi:[1,0]
	v_pk_mul_f32 v[18:19], v[18:19], v[142:143] op_sel_hi:[1,0]
	v_pk_mul_f32 v[12:13], v[12:13], v[142:143] op_sel_hi:[1,0]
	v_pk_mul_f32 v[14:15], v[14:15], v[142:143] op_sel_hi:[1,0]
	v_exp_f32_e32 v143, v113
	v_sub_f32_e32 v113, v129, v112
	v_pk_fma_f32 v[16:17], v[44:45], v[144:145], v[16:17] op_sel_hi:[1,0,1]
	v_pk_fma_f32 v[18:19], v[46:47], v[144:145], v[18:19] op_sel_hi:[1,0,1]
	v_pk_fma_f32 v[12:13], v[48:49], v[144:145], v[12:13] op_sel_hi:[1,0,1]
	v_pk_fma_f32 v[14:15], v[50:51], v[144:145], v[14:15] op_sel_hi:[1,0,1]
	v_exp_f32_e32 v145, v113
	v_sub_f32_e32 v113, v172, v112
	v_pk_fma_f32 v[16:17], v[60:61], v[146:147], v[16:17] op_sel_hi:[1,0,1]
	v_pk_fma_f32 v[18:19], v[62:63], v[146:147], v[18:19] op_sel_hi:[1,0,1]
	v_pk_fma_f32 v[12:13], v[64:65], v[146:147], v[12:13] op_sel_hi:[1,0,1]
	v_pk_fma_f32 v[14:15], v[66:67], v[146:147], v[14:15] op_sel_hi:[1,0,1]
	v_exp_f32_e32 v147, v113
	v_sub_f32_e32 v113, v173, v112
	v_pk_fma_f32 v[16:17], v[76:77], v[148:149], v[16:17] op_sel_hi:[1,0,1]
	v_pk_fma_f32 v[18:19], v[78:79], v[148:149], v[18:19] op_sel_hi:[1,0,1]
	v_pk_fma_f32 v[12:13], v[80:81], v[148:149], v[12:13] op_sel_hi:[1,0,1]
	v_pk_fma_f32 v[14:15], v[82:83], v[148:149], v[14:15] op_sel_hi:[1,0,1]
	v_exp_f32_e32 v149, v113
	v_sub_f32_e32 v113, v175, v112
	v_pk_fma_f32 v[16:17], v[92:93], v[166:167], v[16:17] op_sel_hi:[1,0,1]
	v_pk_fma_f32 v[18:19], v[94:95], v[166:167], v[18:19] op_sel_hi:[1,0,1]
	v_pk_fma_f32 v[12:13], v[96:97], v[166:167], v[12:13] op_sel_hi:[1,0,1]
	v_pk_fma_f32 v[14:15], v[98:99], v[166:167], v[14:15] op_sel_hi:[1,0,1]
	v_exp_f32_e32 v167, v113
	v_pk_fma_f32 v[102:103], v[102:103], v[142:143], v[144:145]
	v_mov_b32_e32 v142, v143
	v_pk_mul_f32 v[4:5], v[4:5], v[142:143] op_sel_hi:[1,0]
	v_mov_b32_e32 v144, v145
	v_pk_mul_f32 v[6:7], v[6:7], v[142:143] op_sel_hi:[1,0]
	v_pk_mul_f32 v[8:9], v[8:9], v[142:143] op_sel_hi:[1,0]
	v_pk_mul_f32 v[10:11], v[10:11], v[142:143] op_sel_hi:[1,0]
	v_pk_add_f32 v[102:103], v[146:147], v[102:103]
	v_pk_fma_f32 v[4:5], v[44:45], v[144:145], v[4:5] op_sel_hi:[1,0,1]
	v_mov_b32_e32 v146, v147
	v_pk_fma_f32 v[6:7], v[46:47], v[144:145], v[6:7] op_sel_hi:[1,0,1]
	v_pk_fma_f32 v[8:9], v[48:49], v[144:145], v[8:9] op_sel_hi:[1,0,1]
	v_pk_fma_f32 v[10:11], v[50:51], v[144:145], v[10:11] op_sel_hi:[1,0,1]
	v_pk_add_f32 v[102:103], v[148:149], v[102:103]
	v_pk_fma_f32 v[4:5], v[60:61], v[146:147], v[4:5] op_sel_hi:[1,0,1]
	v_mov_b32_e32 v148, v149
	v_pk_fma_f32 v[6:7], v[62:63], v[146:147], v[6:7] op_sel_hi:[1,0,1]
	v_pk_fma_f32 v[8:9], v[64:65], v[146:147], v[8:9] op_sel_hi:[1,0,1]
	v_pk_fma_f32 v[10:11], v[66:67], v[146:147], v[10:11] op_sel_hi:[1,0,1]
	v_pk_fma_f32 v[4:5], v[76:77], v[148:149], v[4:5] op_sel_hi:[1,0,1]
	v_mov_b32_e32 v164, v167
	v_pk_fma_f32 v[6:7], v[78:79], v[148:149], v[6:7] op_sel_hi:[1,0,1]
	v_pk_fma_f32 v[8:9], v[80:81], v[148:149], v[8:9] op_sel_hi:[1,0,1]
	v_pk_fma_f32 v[10:11], v[82:83], v[148:149], v[10:11] op_sel_hi:[1,0,1]
	s_addk_i32 s2, 0x80
	v_pk_add_f32 v[102:103], v[166:167], v[102:103]
	v_pk_fma_f32 v[4:5], v[92:93], v[164:165], v[4:5] op_sel_hi:[1,0,1]
	v_pk_fma_f32 v[6:7], v[94:95], v[164:165], v[6:7] op_sel_hi:[1,0,1]
	v_pk_fma_f32 v[8:9], v[96:97], v[164:165], v[8:9] op_sel_hi:[1,0,1]
	v_pk_fma_f32 v[10:11], v[98:99], v[164:165], v[10:11] op_sel_hi:[1,0,1]
	s_cmpk_eq_i32 s2, 0x380
	v_add_u32_e32 v163, 0x200, v163
	s_cbranch_scc1 .LBB0_531
	v_mov_b32_e32 v167, v140
	v_mov_b32_e32 v166, v128
	v_mov_b32_e32 v165, v114
	v_mov_b32_e32 v164, v112
	s_branch .LBB0_471
.LBB0_483:
	s_and_b64 vcc, exec, s[0:1]
	s_cbranch_vccz .LBB0_598
	s_and_b32 s0, s5, 0xffff
	s_mul_i32 s0, s0, 0xaaab
	s_lshr_b32 s39, s0, 21
	s_mul_i32 s0, s39, 48
	s_sub_i32 s0, s5, s0
	s_and_b32 s1, s0, 0xff
	s_mulk_i32 s1, 0xab
	s_load_dwordx4 s[12:15], s[52:53], 0x80
	s_bfe_u32 s2, s1, 0x5000b
	s_mul_i32 s3, s2, 12
	v_mov_b32_e32 v4, v0
	s_sub_i32 s0, s0, s3
	s_sub_i32 s42, 7, s39
	v_readfirstlane_b32 s40, v4
	s_and_b32 s44, s0, 0xff
	s_ashr_i32 s66, s40, 6
	s_mov_b64 s[6:7], 0
	s_waitcnt lgkmcnt(0)
	s_add_u32 s36, s12, s6
	s_addc_u32 s37, s13, s7
	s_add_u32 s68, s36, 0x4c00000
	v_and_b32_e32 v212, 31, v4
	s_addc_u32 s69, s37, 0
	s_lshl_b32 s41, s42, 8
	s_and_b32 s0, s1, 0xf800
	s_or_b32 s5, s0, s41
	v_lshlrev_b32_e32 v3, 3, v212
	v_or_b32_e32 v5, s5, v3
	v_add_u32_e32 v5, s66, v5
	v_mov_b64_e32 v[6:7], s[68:69]
	v_mad_i64_i32 v[6:7], s[0:1], v5, s19, v[6:7]
	v_bfe_u32 v211, v4, 5, 1
	s_lshl_b32 s0, s44, 8
	s_mov_b32 s1, s21
	v_lshl_add_u64 v[6:7], v[6:7], 0, s[0:1]
	v_lshlrev_b32_e32 v198, 4, v211
	v_mov_b32_e32 v199, v2
	v_lshl_add_u64 v[6:7], v[6:7], 0, v[198:199]
	s_lshl_b32 s43, s66, 2
	v_bfe_u32 v197, v4, 4, 2
	global_load_dwordx4 v[162:165], v[6:7], off
	global_load_dwordx4 v[166:169], v[6:7], off offset:32
	global_load_dwordx4 v[170:173], v[6:7], off offset:64
	global_load_dwordx4 v[174:177], v[6:7], off offset:96
	global_load_dwordx4 v[178:181], v[6:7], off offset:128
	global_load_dwordx4 v[182:185], v[6:7], off offset:160
	global_load_dwordx4 v[186:189], v[6:7], off offset:192
	global_load_dwordx4 v[190:193], v[6:7], off offset:224
	v_or_b32_e32 v5, s43, v197
	v_lshlrev_b32_e32 v6, 4, v4
	v_and_b32_e32 v6, 0xf0, v6
	v_lshlrev_b32_e32 v7, 4, v5
	s_movk_i32 s0, 0x70
	v_bitop3_b32 v6, v7, v6, s0 bitop3:0x6c
	s_ashr_i32 s1, s40, 4
	v_lshrrev_b32_e32 v8, 1, v6
	s_and_b32 s3, s1, 0x3ffffff0
	v_lshrrev_b32_e32 v6, 2, v4
	v_lshrrev_b32_e32 v199, 1, v4
	s_lshr_b32 s1, s1, 1
	s_lshl_b32 s0, s66, 1
	v_and_or_b32 v6, v6, 3, s3
	v_and_b32_e32 v7, 8, v199
	s_and_b32 s1, s1, 4
	s_lshl_b32 s20, s44, 7
	v_or3_b32 v6, v6, v7, s1
	v_and_or_b32 v7, s0, 2, v211
	v_lshlrev_b32_e32 v210, 3, v4
	v_lshlrev_b32_e32 v7, 5, v7
	v_and_b32_e32 v9, 24, v210
	s_add_i32 s0, s20, 0xc00
	s_ashr_i32 s67, s66, 31
	v_lshlrev_b32_e32 v10, 2, v6
	v_or3_b32 v6, v7, v9, s0
	v_mov_b32_e32 v7, v2
	s_movk_i32 s3, 0x1800
	s_mul_i32 s2, s2, 0x1800000
	v_mad_i64_i32 v[200:201], s[0:1], v10, s3, v[6:7]
	s_add_u32 s70, s68, s2
	v_lshlrev_b32_e32 v5, 2, v5
	s_addc_u32 s71, s69, 0
	s_lshl_b32 s0, s66, 10
	v_mov_b64_e32 v[6:7], s[20:21]
	s_add_i32 s38, s0, 0
	v_mad_i64_i32 v[202:203], s[0:1], v5, s3, v[6:7]
	v_or_b32_e32 v202, v202, v8
	v_lshl_add_u64 v[6:7], v[202:203], 1, s[70:71]
	s_mov_b64 s[0:1], 0xc00
	v_lshl_add_u64 v[8:9], v[6:7], 0, s[0:1]
	s_add_i32 s0, s38, 0x8000
	s_mov_b32 m0, s38
	v_lshl_add_u64 v[10:11], v[200:201], 1, s[70:71]
	global_load_lds_dwordx4 v[8:9], off
	s_mov_b32 m0, s0
	s_mov_b64 s[0:1], 0x3c00
	global_load_lds_dwordx4 v[10:11], off
	v_lshl_add_u64 v[8:9], v[6:7], 0, s[0:1]
	s_add_i32 m0, s38, 0x2000
	s_mov_b64 s[0:1], 0x3000
	global_load_lds_dwordx4 v[8:9], off
	v_lshl_add_u64 v[8:9], v[10:11], 0, s[0:1]
	s_add_i32 m0, s38, 0xa000
	s_mov_b64 s[0:1], 0x6c00
	global_load_lds_dwordx4 v[8:9], off
	v_lshl_add_u64 v[8:9], v[6:7], 0, s[0:1]
	s_add_i32 m0, s38, 0x4000
	s_mov_b64 s[0:1], 0x6000
	global_load_lds_dwordx4 v[8:9], off
	v_lshl_add_u64 v[8:9], v[10:11], 0, s[0:1]
	s_add_i32 m0, s38, 0xc000
	s_mov_b64 s[0:1], 0x9c00
	global_load_lds_dwordx4 v[8:9], off
	v_lshl_add_u64 v[6:7], v[6:7], 0, s[0:1]
	s_add_i32 m0, s38, 0x6000
	s_mov_b64 s[0:1], 0x9000
	global_load_lds_dwordx4 v[6:7], off
	v_lshl_add_u64 v[6:7], v[10:11], 0, s[0:1]
	s_add_i32 m0, s38, 0xe000
	s_movk_i32 s0, 0xa80
	global_load_lds_dwordx4 v[6:7], off
	v_cmp_gt_i32_e32 vcc, s0, v4
	s_and_saveexec_b64 s[0:1], vcc
	s_cbranch_execz .LBB0_497
	v_max_i32_e32 v5, 0x880, v4
	v_sub_u32_e32 v5, v5, v4
	v_add_u32_e32 v5, 0x1ff, v5
	s_movk_i32 s2, 0x1ff
	v_cmp_lt_u32_e32 vcc, s2, v5
	s_mov_b64 s[2:3], -1
	v_mov_b32_e32 v6, v4
	s_and_saveexec_b64 s[12:13], vcc
	s_cbranch_execz .LBB0_494
	s_mul_i32 s2, s44, 0x2a00
	v_lshrrev_b32_e32 v8, 9, v5
	s_add_u32 s2, s36, s2
	s_addc_u32 s3, s37, 0
	v_add_u32_e32 v6, -1, v8
	s_add_u32 s14, s2, 0x2900000
	v_add_u32_e32 v5, 0x200, v4
	v_lshrrev_b32_e32 v7, 1, v6
	s_addc_u32 s15, s3, 0
	v_add_u32_e32 v9, 1, v7
	v_cmp_lt_u32_e32 vcc, 13, v6
	v_mov_b32_e32 v12, 0
	v_mov_b64_e32 v[6:7], v[4:5]
	s_and_saveexec_b64 s[24:25], vcc
	s_cbranch_execz .LBB0_490
	v_and_b32_e32 v10, -8, v9
	v_lshl_add_u32 v11, v4, 2, s51
	s_mov_b32 s2, 0
	s_mov_b64 s[72:73], 0
	v_mov_b64_e32 v[6:7], v[4:5]

.LBB0_601:
	s_barrier
	s_and_saveexec_b64 s[10:11], s[48:49]
	s_cbranch_execz .LBB0_607
	s_load_dwordx4 s[16:19], s[52:53], 0x80
	s_waitcnt lgkmcnt(0)
	global_load_dword v8, v3, s[16:17] offset:512 sc1
	s_waitcnt vmcnt(0)
	v_cmp_lt_u32_e32 vcc, s4, v8
	v_mov_b32_e32 v8, 0x600
	s_cbranch_vccnz .LBB0_606
	s_mov_b64 s[30:31], exec
	v_mbcnt_lo_u32_b32 v8, s30, 0
	v_mbcnt_hi_u32_b32 v8, s31, v8
	v_cmp_eq_u32_e32 vcc, 0, v8
	s_and_saveexec_b64 s[28:29], vcc
	s_cbranch_execz .LBB0_605
	s_load_dwordx4 s[16:19], s[52:53], 0x80
	s_bcnt1_i32_b64 s9, s[30:31]
	v_mov_b32_e32 v9, s9
	s_waitcnt lgkmcnt(0)
	global_atomic_add v9, v3, v9, s[16:17] offset:768 sc0

.LBB0_607:
	s_or_b64 exec, exec, s[10:11]
	s_waitcnt lgkmcnt(0)
	s_barrier
	ds_read_b32 v8, v1
	s_mov_b64 s[10:11], -1
	s_waitcnt lgkmcnt(0)
	v_readfirstlane_b32 s9, v8
	s_cmpk_gt_i32 s9, 0x5ff
	s_cbranch_scc1 .LBB0_600
	s_mul_hi_i32 s10, s9, 0x2aaaaaab
	s_lshr_b32 s11, s10, 31
	s_add_i32 s16, s10, s11
	s_mul_i32 s10, s16, 6
	s_sub_i32 s9, s9, s10
	s_ashr_i32 s17, s16, 3
	s_add_i32 s9, s9, 6
	v_mad_i64_i32 v[8:9], s[10:11], s17, v2, v[4:5]
	s_and_b32 s16, s16, 7
	v_mad_i64_i32 v[80:81], s[10:11], s17, v2, v[6:7]
	s_mul_i32 s16, s16, 0x24000
	s_mul_hi_u32 s11, s9, 0x3000
	s_mulk_i32 s9, 0x3000
	s_add_u32 s10, s9, s16
	s_addc_u32 s11, s11, 0
	s_lshl_b64 s[16:17], s[10:11], 4
	s_mov_b32 s10, s8
	s_mov_b32 s11, s8
	v_lshl_add_u64 v[48:49], v[8:9], 0, s[0:1]
	s_mov_b32 s9, s8
	v_mov_b64_e32 v[14:15], s[10:11]
	s_waitcnt vmcnt(0)
	v_lshl_add_u64 v[44:45], v[48:49], 0, s[16:17]
	v_mov_b64_e32 v[12:13], s[8:9]
	v_mov_b64_e32 v[18:19], s[10:11]
	global_load_dwordx4 v[12:15], v[44:45], off sc0 sc1 nt
	v_lshl_add_u64 v[20:21], v[44:45], 0, s[2:3]
	v_mov_b64_e32 v[16:17], s[8:9]
	global_load_dwordx4 v[16:19], v[20:21], off sc0 sc1 nt
	v_mov_b64_e32 v[22:23], s[10:11]
	v_lshl_add_u64 v[24:25], v[44:45], 0, s[6:7]
	v_mov_b64_e32 v[20:21], s[8:9]
	global_load_dwordx4 v[20:23], v[24:25], off sc0 sc1 nt
	v_mov_b64_e32 v[26:27], s[10:11]
	v_lshl_add_u64 v[28:29], v[44:45], 0, s[12:13]
	v_mov_b64_e32 v[24:25], s[8:9]
	global_load_dwordx4 v[24:27], v[28:29], off sc0 sc1 nt
	v_mov_b64_e32 v[30:31], s[10:11]
	v_lshl_add_u64 v[32:33], v[44:45], 0, s[14:15]
	v_mov_b64_e32 v[28:29], s[8:9]
	global_load_dwordx4 v[28:31], v[32:33], off sc0 sc1 nt
	v_mov_b64_e32 v[34:35], s[10:11]
	v_lshl_add_u64 v[36:37], v[44:45], 0, s[20:21]
	v_mov_b64_e32 v[32:33], s[8:9]
	global_load_dwordx4 v[32:35], v[36:37], off sc0 sc1 nt
	v_mov_b64_e32 v[38:39], s[10:11]
	v_lshl_add_u64 v[40:41], v[44:45], 0, s[0:1]
	v_mov_b64_e32 v[36:37], s[8:9]
	global_load_dwordx4 v[36:39], v[40:41], off sc0 sc1 nt
	v_mov_b64_e32 v[42:43], s[10:11]
	v_lshl_add_u64 v[46:47], v[44:45], 0, s[24:25]
	v_mov_b64_e32 v[40:41], s[8:9]
	v_mov_b64_e32 v[8:9], s[8:9]
	global_load_dwordx4 v[40:43], v[46:47], off sc0 sc1 nt
	v_lshl_add_u64 v[50:51], v[44:45], 0, s[26:27]
	v_mov_b64_e32 v[46:47], s[10:11]
	v_mov_b64_e32 v[10:11], s[10:11]
	v_mov_b64_e32 v[44:45], s[8:9]
	s_add_u32 s10, s16, 0x12000
	s_addc_u32 s11, s17, 0
	global_load_dwordx4 v[44:47], v[50:51], off sc0 sc1 nt
	v_lshl_add_u64 v[82:83], v[48:49], 0, s[10:11]
	v_mov_b64_e32 v[50:51], v[10:11]
	v_mov_b64_e32 v[48:49], v[8:9]
	v_mov_b64_e32 v[54:55], v[10:11]
	global_load_dwordx4 v[48:51], v[82:83], off sc0 sc1 nt
	v_lshl_add_u64 v[56:57], v[82:83], 0, s[2:3]
	v_mov_b64_e32 v[52:53], v[8:9]
	global_load_dwordx4 v[52:55], v[56:57], off sc0 sc1 nt
	v_mov_b64_e32 v[58:59], v[10:11]
	v_lshl_add_u64 v[60:61], v[82:83], 0, s[6:7]
	v_mov_b64_e32 v[56:57], v[8:9]
	global_load_dwordx4 v[56:59], v[60:61], off sc0 sc1 nt
	v_mov_b64_e32 v[62:63], v[10:11]
	v_lshl_add_u64 v[64:65], v[82:83], 0, s[12:13]
	v_mov_b64_e32 v[60:61], v[8:9]
	global_load_dwordx4 v[60:63], v[64:65], off sc0 sc1 nt
	v_mov_b64_e32 v[66:67], v[10:11]
	v_lshl_add_u64 v[68:69], v[82:83], 0, s[14:15]
	v_mov_b64_e32 v[64:65], v[8:9]
	global_load_dwordx4 v[64:67], v[68:69], off sc0 sc1 nt
	v_mov_b64_e32 v[70:71], v[10:11]
	v_lshl_add_u64 v[72:73], v[82:83], 0, s[20:21]
	v_mov_b64_e32 v[68:69], v[8:9]
	global_load_dwordx4 v[68:71], v[72:73], off sc0 sc1 nt
	v_mov_b64_e32 v[74:75], v[10:11]
	v_lshl_add_u64 v[76:77], v[82:83], 0, s[0:1]
	v_mov_b64_e32 v[72:73], v[8:9]
	global_load_dwordx4 v[72:75], v[76:77], off sc0 sc1 nt
	v_mov_b64_e32 v[78:79], v[10:11]
	v_mov_b64_e32 v[76:77], v[8:9]
	v_lshl_add_u64 v[84:85], v[82:83], 0, s[24:25]
	global_load_dwordx4 v[76:79], v[84:85], off sc0 sc1 nt
	v_lshl_add_u64 v[82:83], v[82:83], 0, s[26:27]
	global_load_dwordx4 v[8:11], v[82:83], off sc0 sc1 nt
	s_waitcnt vmcnt(9)
	v_lshl_add_u64 v[82:83], v[80:81], 0, s[16:17]
	global_store_dwordx4 v[82:83], v[12:15], off nt
	s_nop 1
	v_lshl_add_u64 v[12:13], v[82:83], 0, s[2:3]
	global_store_dwordx4 v[12:13], v[16:19], off nt
	s_nop 1
	v_lshl_add_u64 v[12:13], v[82:83], 0, s[6:7]
	global_store_dwordx4 v[12:13], v[20:23], off nt
	s_nop 1
	v_lshl_add_u64 v[12:13], v[82:83], 0, s[12:13]
	global_store_dwordx4 v[12:13], v[24:27], off nt
	s_nop 1
	v_lshl_add_u64 v[12:13], v[82:83], 0, s[14:15]
	global_store_dwordx4 v[12:13], v[28:31], off nt
	s_nop 1
	v_lshl_add_u64 v[12:13], v[82:83], 0, s[20:21]
	global_store_dwordx4 v[12:13], v[32:35], off nt
	s_nop 1
	v_lshl_add_u64 v[12:13], v[82:83], 0, s[0:1]
	global_store_dwordx4 v[12:13], v[36:39], off nt
	s_nop 1
	v_lshl_add_u64 v[12:13], v[82:83], 0, s[24:25]
	global_store_dwordx4 v[12:13], v[40:43], off nt
	s_nop 1
	v_lshl_add_u64 v[12:13], v[82:83], 0, s[26:27]
	global_store_dwordx4 v[12:13], v[44:47], off nt
	s_nop 1
	s_waitcnt vmcnt(0)
	v_lshl_add_u64 v[12:13], v[80:81], 0, s[10:11]
	global_store_dwordx4 v[12:13], v[48:51], off nt
	s_nop 1
	v_lshl_add_u64 v[14:15], v[12:13], 0, s[2:3]
	global_store_dwordx4 v[14:15], v[52:55], off nt
	s_nop 1
	v_lshl_add_u64 v[14:15], v[12:13], 0, s[6:7]
	global_store_dwordx4 v[14:15], v[56:59], off nt
	s_nop 1
	v_lshl_add_u64 v[14:15], v[12:13], 0, s[12:13]
	global_store_dwordx4 v[14:15], v[60:63], off nt
	s_nop 1
	v_lshl_add_u64 v[14:15], v[12:13], 0, s[14:15]
	global_store_dwordx4 v[14:15], v[64:67], off nt
	s_nop 1
	v_lshl_add_u64 v[14:15], v[12:13], 0, s[20:21]
	global_store_dwordx4 v[14:15], v[68:71], off nt
	s_nop 1
	v_lshl_add_u64 v[14:15], v[12:13], 0, s[0:1]
	global_store_dwordx4 v[14:15], v[72:75], off nt
	s_nop 1
	v_lshl_add_u64 v[14:15], v[12:13], 0, s[24:25]
	global_store_dwordx4 v[14:15], v[76:79], off nt
	s_nop 1
	v_lshl_add_u64 v[12:13], v[12:13], 0, s[26:27]
	global_store_dwordx4 v[12:13], v[8:11], off nt
	s_nop 1
	s_waitcnt vmcnt(0)
	s_mov_b64 s[10:11], 0
	s_branch .LBB0_600

.LBB0_727:
	s_or_b64 exec, exec, s[2:3]
	v_readlane_b32 s0, v248, 0
	v_lshlrev_b32_e32 v0, 4, v0
	v_mov_b32_e32 v1, 0
	v_readlane_b32 s1, v248, 1
	v_readlane_b32 s2, v248, 2
	v_readlane_b32 s3, v248, 3
	v_readlane_b32 s4, v248, 4
	v_readlane_b32 s5, v248, 5
	v_readlane_b32 s6, v248, 6
	v_readlane_b32 s7, v248, 7
	v_readlane_b32 s8, v248, 8
	v_readlane_b32 s9, v248, 9
	v_readlane_b32 s10, v248, 10
	v_readlane_b32 s11, v248, 11
	v_readlane_b32 s12, v248, 12
	v_readlane_b32 s13, v248, 13
	v_readlane_b32 s14, v248, 14
	v_readlane_b32 s15, v248, 15
	v_lshl_add_u64 v[2:3], s[6:7], 0, v[0:1]
	v_readlane_b32 s0, v248, 16
	v_readlane_b32 s1, v248, 17
	v_readlane_b32 s5, v248, 21
	v_readlane_b32 s14, v248, 30
	v_readlane_b32 s15, v248, 31
	v_readlane_b32 s4, v248, 20
	v_readlane_b32 s6, v248, 22
	v_readlane_b32 s7, v248, 23
	v_readlane_b32 s8, v248, 24
	v_readlane_b32 s9, v248, 25
	v_readlane_b32 s10, v248, 26
	v_readlane_b32 s11, v248, 27
	v_readlane_b32 s12, v248, 28
	v_readlane_b32 s13, v248, 29
	v_lshl_add_u64 v[4:5], s[14:15], 0, v[0:1]
	s_mov_b64 s[0:1], 0xa31c000
	s_add_i32 s5, 0, 0x23200
	v_lshl_add_u64 v[4:5], v[4:5], 0, s[0:1]
	s_movk_i32 s4, 0x600
	s_mov_b32 s0, 0
	v_mov_b32_e32 v0, s5
	s_mov_b64 s[6:7], 0xc000
	s_mov_b64 s[8:9], 0x2000
	s_mov_b64 s[10:11], 0x4000
	s_mov_b64 s[12:13], 0x6000
	s_mov_b64 s[14:15], 0x8000
	s_mov_b64 s[16:17], 0xa000
	s_mov_b64 s[18:19], 0xe000
	s_mov_b64 s[20:21], 0x10000
	v_mov_b32_e32 v6, 0x1800000
	v_readlane_b32 s2, v248, 18
	v_readlane_b32 s3, v248, 19
	s_branch .LBB0_729

.LBB0_733:
	s_or_b64 exec, exec, s[2:3]
	s_waitcnt lgkmcnt(0)
	s_barrier
	ds_read_b32 v7, v0
	s_mov_b64 s[2:3], -1
	s_waitcnt lgkmcnt(0)
	v_readfirstlane_b32 s1, v7
	s_cmpk_gt_i32 s1, 0x5ff
	s_cbranch_scc1 .LBB0_728
	s_mul_hi_i32 s2, s1, 0x2aaaaaab
	s_lshr_b32 s3, s2, 31
	s_add_i32 s22, s2, s3
	s_mul_i32 s2, s22, 6
	s_sub_i32 s1, s1, s2
	s_ashr_i32 s23, s22, 3
	s_add_i32 s1, s1, 6
	v_mad_i64_i32 v[8:9], s[2:3], s23, v6, v[2:3]
	s_and_b32 s22, s22, 7
	v_mad_i64_i32 v[80:81], s[2:3], s23, v6, v[4:5]
	s_mul_i32 s22, s22, 0x24000
	s_mul_hi_u32 s3, s1, 0x3000
	s_mulk_i32 s1, 0x3000
	s_add_u32 s2, s1, s22
	s_addc_u32 s3, s3, 0
	s_lshl_b64 s[22:23], s[2:3], 4
	s_mov_b32 s2, s0
	s_mov_b32 s3, s0
	v_lshl_add_u64 v[48:49], v[8:9], 0, s[6:7]
	s_mov_b32 s1, s0
	v_mov_b64_e32 v[14:15], s[2:3]
	s_waitcnt vmcnt(0)
	v_lshl_add_u64 v[44:45], v[48:49], 0, s[22:23]
	v_mov_b64_e32 v[12:13], s[0:1]
	v_mov_b64_e32 v[18:19], s[2:3]
	global_load_dwordx4 v[12:15], v[44:45], off sc0 sc1 nt
	v_lshl_add_u64 v[20:21], v[44:45], 0, s[8:9]
	v_mov_b64_e32 v[16:17], s[0:1]
	global_load_dwordx4 v[16:19], v[20:21], off sc0 sc1 nt
	v_mov_b64_e32 v[22:23], s[2:3]
	v_lshl_add_u64 v[24:25], v[44:45], 0, s[10:11]
	v_mov_b64_e32 v[20:21], s[0:1]
	global_load_dwordx4 v[20:23], v[24:25], off sc0 sc1 nt
	v_mov_b64_e32 v[26:27], s[2:3]
	v_lshl_add_u64 v[28:29], v[44:45], 0, s[12:13]
	v_mov_b64_e32 v[24:25], s[0:1]
	global_load_dwordx4 v[24:27], v[28:29], off sc0 sc1 nt
	v_mov_b64_e32 v[30:31], s[2:3]
	v_lshl_add_u64 v[32:33], v[44:45], 0, s[14:15]
	v_mov_b64_e32 v[28:29], s[0:1]
	global_load_dwordx4 v[28:31], v[32:33], off sc0 sc1 nt
	v_mov_b64_e32 v[34:35], s[2:3]
	v_lshl_add_u64 v[36:37], v[44:45], 0, s[16:17]
	v_mov_b64_e32 v[32:33], s[0:1]
	global_load_dwordx4 v[32:35], v[36:37], off sc0 sc1 nt
	v_mov_b64_e32 v[38:39], s[2:3]
	v_lshl_add_u64 v[40:41], v[44:45], 0, s[6:7]
	v_mov_b64_e32 v[36:37], s[0:1]
	global_load_dwordx4 v[36:39], v[40:41], off sc0 sc1 nt
	v_mov_b64_e32 v[42:43], s[2:3]
	v_lshl_add_u64 v[46:47], v[44:45], 0, s[18:19]
	v_mov_b64_e32 v[40:41], s[0:1]
	v_mov_b64_e32 v[10:11], s[2:3]
	global_load_dwordx4 v[40:43], v[46:47], off sc0 sc1 nt
	v_lshl_add_u64 v[50:51], v[44:45], 0, s[20:21]
	v_mov_b64_e32 v[46:47], s[2:3]
	v_mov_b64_e32 v[8:9], s[0:1]
	v_mov_b64_e32 v[44:45], s[0:1]
	s_add_u32 s2, s22, 0x12000
	s_addc_u32 s3, s23, 0
	global_load_dwordx4 v[44:47], v[50:51], off sc0 sc1 nt
	v_lshl_add_u64 v[82:83], v[48:49], 0, s[2:3]
	v_mov_b64_e32 v[50:51], v[10:11]
	v_mov_b64_e32 v[48:49], v[8:9]
	v_mov_b64_e32 v[54:55], v[10:11]
	global_load_dwordx4 v[48:51], v[82:83], off sc0 sc1 nt
	v_lshl_add_u64 v[56:57], v[82:83], 0, s[8:9]
	v_mov_b64_e32 v[52:53], v[8:9]
	global_load_dwordx4 v[52:55], v[56:57], off sc0 sc1 nt
	v_mov_b64_e32 v[58:59], v[10:11]
	v_lshl_add_u64 v[60:61], v[82:83], 0, s[10:11]
	v_mov_b64_e32 v[56:57], v[8:9]
	global_load_dwordx4 v[56:59], v[60:61], off sc0 sc1 nt
	v_mov_b64_e32 v[62:63], v[10:11]
	v_lshl_add_u64 v[64:65], v[82:83], 0, s[12:13]
	v_mov_b64_e32 v[60:61], v[8:9]
	global_load_dwordx4 v[60:63], v[64:65], off sc0 sc1 nt
	v_mov_b64_e32 v[66:67], v[10:11]
	v_lshl_add_u64 v[68:69], v[82:83], 0, s[14:15]
	v_mov_b64_e32 v[64:65], v[8:9]
	global_load_dwordx4 v[64:67], v[68:69], off sc0 sc1 nt
	v_mov_b64_e32 v[70:71], v[10:11]
	v_lshl_add_u64 v[72:73], v[82:83], 0, s[16:17]
	v_mov_b64_e32 v[68:69], v[8:9]
	global_load_dwordx4 v[68:71], v[72:73], off sc0 sc1 nt
	v_mov_b64_e32 v[74:75], v[10:11]
	v_lshl_add_u64 v[76:77], v[82:83], 0, s[6:7]
	v_mov_b64_e32 v[72:73], v[8:9]
	global_load_dwordx4 v[72:75], v[76:77], off sc0 sc1 nt
	v_mov_b64_e32 v[78:79], v[10:11]
	v_mov_b64_e32 v[76:77], v[8:9]
	v_lshl_add_u64 v[84:85], v[82:83], 0, s[18:19]
	global_load_dwordx4 v[76:79], v[84:85], off sc0 sc1 nt
	v_lshl_add_u64 v[82:83], v[82:83], 0, s[20:21]
	global_load_dwordx4 v[8:11], v[82:83], off sc0 sc1 nt
	s_waitcnt vmcnt(9)
	v_lshl_add_u64 v[82:83], v[80:81], 0, s[22:23]
	global_store_dwordx4 v[82:83], v[12:15], off nt
	s_nop 1
	v_lshl_add_u64 v[12:13], v[82:83], 0, s[8:9]
	global_store_dwordx4 v[12:13], v[16:19], off nt
	s_nop 1
	v_lshl_add_u64 v[12:13], v[82:83], 0, s[10:11]
	global_store_dwordx4 v[12:13], v[20:23], off nt
	s_nop 1
	v_lshl_add_u64 v[12:13], v[82:83], 0, s[12:13]
	global_store_dwordx4 v[12:13], v[24:27], off nt
	s_nop 1
	v_lshl_add_u64 v[12:13], v[82:83], 0, s[14:15]
	global_store_dwordx4 v[12:13], v[28:31], off nt
	s_nop 1
	v_lshl_add_u64 v[12:13], v[82:83], 0, s[16:17]
	global_store_dwordx4 v[12:13], v[32:35], off nt
	s_nop 1
	v_lshl_add_u64 v[12:13], v[82:83], 0, s[6:7]
	global_store_dwordx4 v[12:13], v[36:39], off nt
	s_nop 1
	v_lshl_add_u64 v[12:13], v[82:83], 0, s[18:19]
	global_store_dwordx4 v[12:13], v[40:43], off nt
	s_nop 1
	v_lshl_add_u64 v[12:13], v[82:83], 0, s[20:21]
	global_store_dwordx4 v[12:13], v[44:47], off nt
	s_nop 1
	s_waitcnt vmcnt(0)
	v_lshl_add_u64 v[12:13], v[80:81], 0, s[2:3]
	global_store_dwordx4 v[12:13], v[48:51], off nt
	s_nop 1
	v_lshl_add_u64 v[14:15], v[12:13], 0, s[8:9]
	global_store_dwordx4 v[14:15], v[52:55], off nt
	s_nop 1
	v_lshl_add_u64 v[14:15], v[12:13], 0, s[10:11]
	global_store_dwordx4 v[14:15], v[56:59], off nt
	s_nop 1
	v_lshl_add_u64 v[14:15], v[12:13], 0, s[12:13]
	global_store_dwordx4 v[14:15], v[60:63], off nt
	s_nop 1
	v_lshl_add_u64 v[14:15], v[12:13], 0, s[14:15]
	global_store_dwordx4 v[14:15], v[64:67], off nt
	s_nop 1
	v_lshl_add_u64 v[14:15], v[12:13], 0, s[16:17]
	global_store_dwordx4 v[14:15], v[68:71], off nt
	s_nop 1
	v_lshl_add_u64 v[14:15], v[12:13], 0, s[6:7]
	global_store_dwordx4 v[14:15], v[72:75], off nt
	s_nop 1
	v_lshl_add_u64 v[14:15], v[12:13], 0, s[18:19]
	global_store_dwordx4 v[14:15], v[76:79], off nt
	s_nop 1
	v_lshl_add_u64 v[12:13], v[12:13], 0, s[20:21]
	global_store_dwordx4 v[12:13], v[8:11], off nt
	s_nop 1
	s_waitcnt vmcnt(0)
	s_add_i32 s4, s4, -1
	s_cmp_eq_u32 s4, 0
	s_cselect_b64 s[2:3], -1, 0
	s_branch .LBB0_728

	.amdhsa_kernel _Z8mega_fwd6Params
		.amdhsa_group_segment_fixed_size 0
		.amdhsa_private_segment_fixed_size 0
		.amdhsa_kernarg_size 400
		.amdhsa_user_sgpr_count 2
		.amdhsa_user_sgpr_dispatch_ptr 0
		.amdhsa_user_sgpr_queue_ptr 0
		.amdhsa_user_sgpr_kernarg_segment_ptr 1
		.amdhsa_user_sgpr_dispatch_id 0
		.amdhsa_user_sgpr_kernarg_preload_length 0
		.amdhsa_user_sgpr_kernarg_preload_offset 0
		.amdhsa_user_sgpr_private_segment_size 0
		.amdhsa_uses_dynamic_stack 0
		.amdhsa_enable_private_segment 0
		.amdhsa_system_sgpr_workgroup_id_x 1
		.amdhsa_system_sgpr_workgroup_id_y 0
		.amdhsa_system_sgpr_workgroup_id_z 0
		.amdhsa_system_sgpr_workgroup_info 0
		.amdhsa_system_vgpr_workitem_id 0
		.amdhsa_next_free_vgpr 249
		.amdhsa_next_free_sgpr 102
		.amdhsa_accum_offset 252
		.amdhsa_reserve_vcc 1
		.amdhsa_float_round_mode_32 0
		.amdhsa_float_round_mode_16_64 0
		.amdhsa_float_denorm_mode_32 3
		.amdhsa_float_denorm_mode_16_64 3
		.amdhsa_dx10_clamp 1
		.amdhsa_ieee_mode 1
		.amdhsa_fp16_overflow 0
		.amdhsa_tg_split 0
		.amdhsa_exception_fp_ieee_invalid_op 0
		.amdhsa_exception_fp_denorm_src 0
		.amdhsa_exception_fp_ieee_div_zero 0
		.amdhsa_exception_fp_ieee_overflow 0
		.amdhsa_exception_fp_ieee_underflow 0
		.amdhsa_exception_fp_ieee_inexact 0
		.amdhsa_exception_int_div_zero 0
	.end_amdhsa_kernel

amdhsa.kernels:
  - .agpr_count:     0
    .args:
      - .offset:         0
        .size:           144
        .value_kind:     by_value
      - .offset:         144
        .size:           4
        .value_kind:     hidden_block_count_x
      - .offset:         148
        .size:           4
        .value_kind:     hidden_block_count_y
      - .offset:         152
        .size:           4
        .value_kind:     hidden_block_count_z
      - .offset:         156
        .size:           2
        .value_kind:     hidden_group_size_x
      - .offset:         158
        .size:           2
        .value_kind:     hidden_group_size_y
      - .offset:         160
        .size:           2
        .value_kind:     hidden_group_size_z
      - .offset:         162
        .size:           2
        .value_kind:     hidden_remainder_x
      - .offset:         164
        .size:           2
        .value_kind:     hidden_remainder_y
      - .offset:         166
        .size:           2
        .value_kind:     hidden_remainder_z
      - .offset:         184
        .size:           8
        .value_kind:     hidden_global_offset_x
      - .offset:         192
        .size:           8
        .value_kind:     hidden_global_offset_y
      - .offset:         200
        .size:           8
        .value_kind:     hidden_global_offset_z
      - .offset:         208
        .size:           2
        .value_kind:     hidden_grid_dims
      - .offset:         264
        .size:           4
        .value_kind:     hidden_dynamic_lds_size
    .group_segment_fixed_size: 0
    .kernarg_segment_align: 8
    .kernarg_segment_size: 400
    .language:       OpenCL C
    .language_version:
      - 2
      - 0
    .max_flat_workgroup_size: 512
    .name:           _Z8mega_fwd6Params
    .private_segment_fixed_size: 0
    .sgpr_count:     108
    .sgpr_spill_count: 57
    .symbol:         _Z8mega_fwd6Params.kd
    .uniform_work_group_size: 1
    .uses_dynamic_stack: false
    .vgpr_count:     249
    .vgpr_spill_count: 0
    .wavefront_size: 64
